# diff+dilated attention unit prologue: tile 0 and tile 1 K/V loads issued together (one exposed round trip instead of two)
# speedup vs baseline: 1.0067x; 1.0067x over previous
; #define LAS __attribute__((address_space(3)))
; #define AT_GLOADK(kt) do { const size_t r_ = rowbase + (size_t)(kt) * 64; \
;         kreg = *(const u32x4*)(Kp + (r_ + lane) * kpitch + wave * 8); \
;         if (MODE == 0 && wave < 4) kreg2 = *(const u32x4*)(proj + (r_ + lane) * NPROJ + 1920 + wave * 8); } while (0)
; #define AT_GLOADV(kt) do { const size_t r_ = rowbase + (size_t)(kt) * 64; \
;         vreg = *(const u32x4*)(Vp + (r_ + 16 * (wave & 3) + (lane >> 2)) * vpitch + (wave >> 2) * 32 + (lane & 3) * 8); } while (0)
; #define AT_LSTOREV(buf) do { LAS unsigned char* d_ = lds + (buf) * AT_BUF; \
;         *(LAS u32x4*)(d_ + AT_V + wave * 1024 + lane * 16) = vreg; } while (0)
; template <int MODE, int NQ>
; __device__ __forceinline__ void attn_unit(LAS unsigned char* lds, const Params& P, int layer, int b, int h, int qb) {
;     ...
;     const int qpos0 = q0 + wave * (32 * NQ) + r32;
;     const int tb0_ = 4 * hi - qpos0 + 2047, ts_ = tb0_ & 3;
;     const LAS unsigned char* tlane = tabb + ts_ * AT_TABC + (tb0_ - ts_) * 4;
;     bf16x8 qf[NC][ND0];
; #pragma unroll
;     for (int jq = 0; jq < NQ; ++jq) {
;         const bf16_t* qrow = Qp + (rowbase + qpos0 + 32 * jq) * qpitch + hi * 8;
; #pragma unroll
;         for (int mp = 0; mp < NMAP; ++mp)
; #pragma unroll
;             for (int d0 = 0; d0 < ND0; ++d0) qf[jq * NMAP + mp][d0] = *(const bf16x8*)(qrow + mp * 32 + d0 * 16);
;     }
;     u32x4 kreg, kreg2 = (u32x4){0u, 0u, 0u, 0u}, vreg;
;     ...
;     float mrun[NC], lrun[NC]; f32x16 o[NC][2];
; #pragma unroll
;     for (int cc = 0; cc < NC; ++cc) { mrun[cc] = -1e20f; lrun[cc] = 0.f; o[cc][0] = f32x16{}; o[cc][1] = f32x16{}; }
;     constexpr int NK = NMAP * ND0;
;     const bf16x8 ones8 = (bf16x8){0x3F80, 0x3F80, 0x3F80, 0x3F80, 0x3F80, 0x3F80, 0x3F80, 0x3F80};
;     const bf16x8 zero8 = (bf16x8){0, 0, 0, 0, 0, 0, 0, 0};
;     bf16x8 kf[NK]; s16x4 vlo[4], vhi[4];
;     ...
;     const int vlane = ((lane >> 4) & 1) * 32 + (lane & 3) * 8 + (4 * hi + ((lane & 15) >> 2)) * 64;
;     const int NT = kt1 - kt0, ks = (MODE != 0) ? (q0 / 64 - kt0) : 0;
;     ...
;     AT_GLOADK(AT_TILE(0)); AT_GLOADV(AT_TILE(0)); AT_LSTOREK(0); AT_LSTOREV(0);
;     if (1 < NT) { AT_GLOADK(AT_TILE(1)); AT_GLOADV(AT_TILE(1)); AT_LSTOREK(1); AT_LSTOREV(1); }
;     __syncthreads();
;     AT_KLOAD(lds, 0);
;     if (wave >= 4) __builtin_amdgcn_s_setprio(1);
.LBB0_406:
	s_or_b64 exec, exec, s[0:1]
	s_ashr_i32 s0, s7, 2
	s_and_b32 s6, s6, 7
	s_ashr_i32 s1, s0, 31
	s_ashr_i32 s7, s5, 6
	s_lshl_b64 s[0:1], s[0:1], 11
	s_lshl_b32 s16, s6, 8
	s_lshl_b32 s14, s4, 7
	s_add_u32 s8, s90, s14
	s_addc_u32 s9, s91, 0
	v_readlane_b32 s10, v254, 40
	s_add_u32 s10, s10, s14
	v_readlane_b32 s11, v254, 41
	s_addc_u32 s11, s11, 0
	v_readlane_b32 s15, v254, 42
	s_add_u32 s14, s15, s14
	v_readlane_b32 s15, v254, 43
	s_addc_u32 s15, s15, 0
	s_lshl_b32 s17, s7, 5
	v_and_b32_e32 v7, 31, v2
	s_add_i32 s17, s17, s16
	v_or_b32_e32 v4, s17, v7
	v_ashrrev_i32_e32 v5, 31, v4
	v_lshl_add_u64 v[176:177], s[0:1], 0, v[4:5]
	v_mov_b64_e32 v[8:9], s[8:9]
	v_bfe_u32 v6, v2, 5, 1
	v_mad_u64_u32 v[8:9], s[8:9], v176, s27, v[8:9]
	v_mad_i32_i24 v9, v177, s27, v9
	v_lshlrev_b32_e32 v0, 4, v6
	v_and_b32_e32 v3, 63, v2
	v_lshl_add_u64 v[8:9], v[8:9], 0, v[0:1]
	v_lshlrev_b32_e32 v0, 3, v2
	s_or_b32 s24, s16, s0
	v_and_b32_e32 v189, 24, v0
	v_or_b32_e32 v0, s24, v3
	v_mov_b64_e32 v[16:17], s[10:11]
	global_load_dwordx4 v[124:127], v[8:9], off
	global_load_dwordx4 v[116:119], v[8:9], off offset:32
	global_load_dwordx4 v[120:123], v[8:9], off offset:64
	global_load_dwordx4 v[112:115], v[8:9], off offset:96
	v_mad_u64_u32 v[8:9], s[8:9], v0, s27, v[16:17]
	s_lshl_b32 s8, s7, 3
	s_ashr_i32 s9, s8, 31
	s_lshl_b64 s[16:17], s[8:9], 1
	s_lshl_b32 s8, s7, 4
	s_and_b32 s8, s8, 48
	s_or_b32 s9, s24, s8
	v_bfe_u32 v5, v2, 2, 4
	v_or_b32_e32 v0, s9, v5
	v_mov_b64_e32 v[18:19], s[14:15]
	v_mad_u64_u32 v[12:13], s[18:19], v0, s27, v[18:19]
	s_ashr_i32 s5, s5, 3
	s_and_b32 s18, s5, 0xffffffe0
	s_ashr_i32 s19, s18, 31
	v_mad_i32_i24 v9, s1, v236, v9
	v_mad_i32_i24 v13, s1, v236, v13
	s_lshl_b64 s[22:23], s[18:19], 1
	v_lshl_add_u64 v[8:9], v[8:9], 0, s[16:17]
	v_lshl_add_u64 v[12:13], v[12:13], 0, s[22:23]
	v_lshlrev_b32_e32 v0, 1, v189
	global_load_dwordx4 v[8:11], v[8:9], off
	v_lshl_add_u64 v[12:13], v[12:13], 0, v[0:1]
	global_load_dwordx4 v[12:15], v[12:13], off
	s_lshl_b32 s5, s7, 10
	s_add_i32 s5, s5, 0
	v_lshl_add_u32 v194, v3, 4, s5
	s_or_b32 s5, s24, 64
	v_lshlrev_b32_e32 v195, 10, v6
	v_lshlrev_b32_e32 v196, 4, v7
	v_add3_u32 v190, 0, v195, v196
	v_or_b32_e32 v224, s5, v3
	s_or_b32 s5, s5, s8
	v_or_b32_e32 v228, s5, v5
	v_mad_u64_u32 v[224:225], s[18:19], v224, s27, v[16:17]
	v_mad_u64_u32 v[228:229], s[18:19], v228, s27, v[18:19]
	v_mad_i32_i24 v225, s1, v236, v225
	v_mad_i32_i24 v229, s1, v236, v229
	v_lshl_add_u64 v[224:225], v[224:225], 0, s[16:17]
	v_lshl_add_u64 v[228:229], v[228:229], 0, s[22:23]
	global_load_dwordx4 v[224:227], v[224:225], off
	v_lshl_add_u64 v[228:229], v[228:229], 0, v[0:1]
	global_load_dwordx4 v[228:231], v[228:229], off
	s_cmp_gt_i32 s7, 3
	s_waitcnt vmcnt(2)
	ds_write_b128 v194, v[8:11]
	ds_write_b128 v194, v[12:15] offset:12288
	s_waitcnt vmcnt(0)
	ds_write_b128 v194, v[224:227] offset:20480
	ds_write_b128 v194, v[228:231] offset:32768
	s_waitcnt lgkmcnt(0)
	s_barrier
	ds_read_b128 v[140:143], v190
	ds_read_b128 v[136:139], v190 offset:2048
	ds_read_b128 v[132:135], v190 offset:4096
	ds_read_b128 v[128:131], v190 offset:6144
	s_cbranch_scc0 .LBB0_408
	s_setprio 1

; #define LAS __attribute__((address_space(3)))
; template <int MODE, int NQ>
; __device__ __forceinline__ void attn_unit(LAS unsigned char* lds, const Params& P, int layer, int b, int h, int qb) {
;     ...
;     int kt0 = 0, kt1 = SEQ / 64;
;     if (MODE == 2) { kt0 = (q0 - 1024) / 64; if (kt0 < 0) kt0 = 0; kt1 = (q0 + QROWS + 1024) / 64; if (kt1 > SEQ / 64) kt1 = SEQ / 64; }
;     LAS unsigned char* tabb = lds + AT_TAB;
;     if (MODE != 0) {
;         const float slope = (MODE == 1) ? exp2f(-(float)(2 * h + 1)) : exp2f(-(float)(2 * h + 2));
;         for (int jj = tid; jj < 4 * 4096; jj += 512) {
;             const int sc_ = jj >> 12, j = (jj & 4095) + sc_;
;             const int d = (j > 2047) ? (j - 2047) : (2047 - j);
;             float v = -slope * LOG2E * (float)d;
;             if (MODE == 2) {
;                 const int mult = (d <= 64 ? 1 : 0) + (((d & 3) == 0 && d <= 256) ? 1 : 0) + (((d & 15) == 0 && d <= 1024) ? 1 : 0);
;                 v = (mult == 0) ? -1e30f : (mult == 1 ? v : (mult == 2 ? v + 1.0f : v + 1.5849625007211562f));
;             }
;             *(LAS float*)(tabb + sc_ * AT_TABC + (jj & 4095) * 4) = v;
;         }
;     }
;     const int qpos0 = q0 + wave * (32 * NQ) + r32;
;     const int tb0_ = 4 * hi - qpos0 + 2047, ts_ = tb0_ & 3;
;     const LAS unsigned char* tlane = tabb + ts_ * AT_TABC + (tb0_ - ts_) * 4;
;     bf16x8 qf[NC][ND0];
; #pragma unroll
;     for (int jq = 0; jq < NQ; ++jq) {
;         const bf16_t* qrow = Qp + (rowbase + qpos0 + 32 * jq) * qpitch + hi * 8;
; #pragma unroll
;         for (int mp = 0; mp < NMAP; ++mp)
; #pragma unroll
;             for (int d0 = 0; d0 < ND0; ++d0) qf[jq * NMAP + mp][d0] = *(const bf16x8*)(qrow + mp * 32 + d0 * 16);
;     }
;     u32x4 kreg, kreg2 = (u32x4){0u, 0u, 0u, 0u}, vreg;
;     ...
;     float mrun[NC], lrun[NC]; f32x16 o[NC][2];
; #pragma unroll
;     for (int cc = 0; cc < NC; ++cc) { mrun[cc] = -1e20f; lrun[cc] = 0.f; o[cc][0] = f32x16{}; o[cc][1] = f32x16{}; }
;     constexpr int NK = NMAP * ND0;
;     const bf16x8 ones8 = (bf16x8){0x3F80, 0x3F80, 0x3F80, 0x3F80, 0x3F80, 0x3F80, 0x3F80, 0x3F80};
;     const bf16x8 zero8 = (bf16x8){0, 0, 0, 0, 0, 0, 0, 0};
;     bf16x8 kf[NK]; s16x4 vlo[4], vhi[4];
;     ...
;     const int vlane = ((lane >> 4) & 1) * 32 + (lane & 3) * 8 + (4 * hi + ((lane & 15) >> 2)) * 64;
;     const int NT = kt1 - kt0, ks = (MODE != 0) ? (q0 / 64 - kt0) : 0;
.LBB0_499:
	s_or_b64 exec, exec, s[0:1]
	s_ashr_i32 s0, s6, 2
	s_ashr_i32 s1, s0, 31
	s_ashr_i32 s20, s18, 6
	s_lshl_b64 s[0:1], s[0:1], 11
	s_lshl_b32 s8, s19, 8
	s_lshl_b32 s14, s9, 7
	v_readlane_b32 s6, v254, 49
	s_add_u32 s6, s6, s14
	v_readlane_b32 s7, v254, 50
	s_addc_u32 s7, s7, 0
	v_readlane_b32 s10, v254, 51
	s_add_u32 s10, s10, s14
	v_readlane_b32 s11, v254, 52
	s_addc_u32 s11, s11, 0
	v_readlane_b32 s15, v254, 53
	s_add_u32 s14, s15, s14
	v_readlane_b32 s15, v254, 54
	s_addc_u32 s15, s15, 0
	s_lshl_b32 s17, s20, 5
	v_and_b32_e32 v7, 31, v2
	s_add_i32 s17, s17, s8
	s_add_i32 s16, s8, 0xfffffc00
	v_or_b32_e32 v4, s17, v7
	s_ashr_i32 s16, s16, 6
	v_ashrrev_i32_e32 v5, 31, v4
	s_max_i32 s24, s16, 0
	s_add_i32 s16, s8, 0x500
	v_lshl_add_u64 v[116:117], s[0:1], 0, v[4:5]
	v_mov_b64_e32 v[8:9], s[6:7]
	s_lshr_b32 s16, s16, 6
	v_mad_u64_u32 v[8:9], s[6:7], v116, s27, v[8:9]
	s_min_u32 s16, s16, 32
	s_lshl_b32 s7, s19, 2
	s_sub_i32 s6, s16, s24
	s_sub_i32 s8, s7, s24
	s_cmp_ge_u32 s7, s16
	s_cselect_b32 s16, s6, 0
	s_sub_i32 s16, s7, s16
	s_ashr_i32 s17, s16, 31
	s_lshl_b64 s[16:17], s[16:17], 6
	v_bfe_u32 v6, v2, 5, 1
	s_add_u32 s22, s16, s0
	v_mad_i32_i24 v9, v117, s27, v9
	v_lshlrev_b32_e32 v0, 4, v6
	s_addc_u32 s25, s17, s1
	s_lshl_b32 s21, s20, 4
	v_and_b32_e32 v3, 63, v2
	v_lshl_add_u64 v[8:9], v[8:9], 0, v[0:1]
	v_lshlrev_b32_e32 v0, 3, v2
	s_and_b32 s21, s21, 48
	v_and_b32_e32 v124, 24, v0
	v_or_b32_e32 v0, s22, v3
	v_mov_b64_e32 v[16:17], s[10:11]
	s_or_b32 s22, s22, s21
	v_bfe_u32 v5, v2, 2, 4
	global_load_dwordx4 v[64:67], v[8:9], off
	global_load_dwordx4 v[68:71], v[8:9], off offset:32
	global_load_dwordx4 v[72:75], v[8:9], off offset:64
	global_load_dwordx4 v[76:79], v[8:9], off offset:96
	v_mad_u64_u32 v[8:9], s[16:17], v0, s27, v[16:17]
	v_or_b32_e32 v0, s22, v5
	v_mov_b64_e32 v[18:19], s[14:15]
	v_mad_u64_u32 v[12:13], s[22:23], v0, s27, v[18:19]
	s_ashr_i32 s18, s18, 3
	s_lshl_b32 s16, s20, 3
	s_and_b32 s22, s18, 0xffffffe0
	s_ashr_i32 s17, s16, 31
	s_ashr_i32 s23, s22, 31
	v_mad_i32_i24 v9, s25, v236, v9
	s_lshl_b64 s[16:17], s[16:17], 1
	v_mad_i32_i24 v13, s25, v236, v13
	s_lshl_b64 s[22:23], s[22:23], 1
	v_lshl_add_u64 v[8:9], v[8:9], 0, s[16:17]
	v_lshl_add_u64 v[12:13], v[12:13], 0, s[22:23]
	v_lshlrev_b32_e32 v0, 1, v124
	global_load_dwordx4 v[8:11], v[8:9], off
	v_lshl_add_u64 v[12:13], v[12:13], 0, v[0:1]
	global_load_dwordx4 v[12:15], v[12:13], off
	s_lshl_b32 s18, s20, 10
	s_add_i32 s18, s18, 0
	v_lshl_add_u32 v125, v3, 4, s18
	s_or_b32 s18, s8, 1
	s_cmp_ge_i32 s18, s6
	s_cselect_b32 s25, s6, 0
	s_add_i32 s18, s18, s24
	s_sub_i32 s24, s18, s25
	s_ashr_i32 s25, s24, 31
	s_lshl_b64 s[24:25], s[24:25], 6
	s_add_u32 s18, s24, s0
	s_addc_u32 s35, s25, s1
	v_lshlrev_b32_e32 v126, 10, v6
	v_lshlrev_b32_e32 v127, 4, v7
	v_add3_u32 v128, 0, v126, v127
	v_or_b32_e32 v140, s18, v3
	v_mad_u64_u32 v[140:141], s[24:25], v140, s27, v[16:17]
	v_mad_i32_i24 v141, s35, v236, v141
	v_lshl_add_u64 v[140:141], v[140:141], 0, s[16:17]
	s_or_b32 s18, s18, s21
	global_load_dwordx4 v[80:83], v[140:141], off
	v_or_b32_e32 v140, s18, v5
	v_mad_u64_u32 v[140:141], s[24:25], v140, s27, v[18:19]
	v_mad_i32_i24 v141, s35, v236, v141
	v_lshl_add_u64 v[140:141], v[140:141], 0, s[22:23]
	v_lshl_add_u64 v[140:141], v[140:141], 0, v[0:1]
	global_load_dwordx4 v[84:87], v[140:141], off
	s_cmp_gt_i32 s20, 3
	s_waitcnt vmcnt(3)
	ds_write_b128 v125, v[8:11]
	s_waitcnt vmcnt(2)
	ds_write_b128 v125, v[12:15] offset:12288
	s_waitcnt vmcnt(1)
	ds_write_b128 v125, v[80:83] offset:20480
	s_waitcnt vmcnt(0)
	ds_write_b128 v125, v[84:87] offset:32768
	s_waitcnt lgkmcnt(0)
	s_barrier
	ds_read_b128 v[96:99], v128
	ds_read_b128 v[100:103], v128 offset:2048
	ds_read_b128 v[92:95], v128 offset:4096
	ds_read_b128 v[88:91], v128 offset:6144
	s_cbranch_scc0 .LBB0_501
	s_setprio 1
